# compress item: agent-scope threadfence between its two GEMMs replaced by workgroup-scope wait (same-WG producer/consumer) + in-register top-k
# speedup vs baseline: 1.0168x; 1.0129x over previous
; template <int BN, typename AF>
; DEVI void gemm_core(f32x4 (&acc)[BN / 32][4], AF arow, long a_kstride, const bfu* __restrict__ Bt, int ldb, int nkt,
;                     bfu* lds) {
;     ...
;   G_LOAD(0, 0);
;   if (nkt > 1) G_LOAD(1, 1);
;   L_STORE(0, As, Bs);
;   __syncthreads();
; #pragma unroll 1
;   for (int kt = 0; kt < nkt; kt += 2) {
;     if (kt + 2 < nkt) G_LOAD(0, kt + 2);
;     COMPUTE(0);
;     if (kt + 1 < nkt) L_STORE(1, As + 128 * LS, Bs + BN * LS);
;     __syncthreads();
;     if (kt + 1 < nkt) {
;       if (kt + 3 < nkt) G_LOAD(1, kt + 3);
;       COMPUTE(1);
;       if (kt + 2 < nkt) L_STORE(0, As, Bs);
; DEVI void compress_item(const Params& p, int l, int ci, char* lds) {
;     ...
;   __threadfence();
;   __syncthreads();
;   float* outs = (float*)lds;
;   {
;     f32x4 acc2[2][4];
;     zero_acc<2>(acc2);
;     gemm_core<64>(acc2, [&](int r) { return (const bfu*)chid + r * 128; }, 64,
;                   (const bfu*)(p.ws + OFF_CW2) + (long)kv * 64 * 128, 128, 2, (bfu*)lds);
.LBB0_639:
	v_mov_b32_e32 v36, v221
	s_waitcnt vmcnt(0) lgkmcnt(0)
	s_barrier
	s_lshl_b64 s[36:37], s[48:49], 14
	v_lshlrev_b32_e32 v4, 4, v36
	v_and_b32_e32 v0, 0x70, v4
	v_and_b32_e32 v4, 0xffffff80, v4
	v_add_u32_e32 v6, 0x1000, v4
	v_readlane_b32 s11, v243, 32
	v_lshl_add_u64 v[2:3], s[0:1], 0, v[0:1]
	v_ashrrev_i32_e32 v5, 31, v4
	v_ashrrev_i32_e32 v7, 31, v6
	s_add_u32 s36, s11, s36
	v_readlane_b32 s11, v243, 33
	v_lshl_add_u64 v[30:31], v[4:5], 1, v[2:3]
	v_lshl_add_u64 v[46:47], v[6:7], 1, v[2:3]
	v_add_u32_e32 v6, 0x2000, v4
	v_add_u32_e32 v4, 0x3000, v4
	v_ashrrev_i32_e32 v26, 3, v36
	s_addc_u32 s37, s11, s37
	v_ashrrev_i32_e32 v7, 31, v6
	v_ashrrev_i32_e32 v5, 31, v4
	v_ashrrev_i32_e32 v27, 31, v26
	v_lshl_add_u64 v[42:43], v[6:7], 1, v[2:3]
	v_lshl_add_u64 v[38:39], v[4:5], 1, v[2:3]
	v_lshl_add_u64 v[2:3], s[36:37], 0, v[0:1]
	v_lshlrev_b64 v[4:5], 8, v[26:27]
	v_lshl_add_u64 v[28:29], v[2:3], 0, v[4:5]
	v_add_u32_e32 v4, 0x100, v36
	v_ashrrev_i32_e32 v32, 3, v4
	v_ashrrev_i32_e32 v33, 31, v32
	v_lshlrev_b64 v[4:5], 8, v[32:33]
	v_lshl_add_u64 v[34:35], v[2:3], 0, v[4:5]
	global_load_dwordx4 v[2:5], v[30:31], off
	global_load_dwordx4 v[6:9], v[46:47], off
	global_load_dwordx4 v[10:13], v[42:43], off
	global_load_dwordx4 v[14:17], v[38:39], off
	global_load_dwordx4 v[18:21], v[28:29], off
	global_load_dwordx4 v[22:25], v[34:35], off
	v_and_b32_e32 v51, 15, v36
	v_add_u32_e32 v27, 0x200, v36
	v_add_u32_e32 v33, 0x300, v36
	v_lshrrev_b32_e32 v52, 1, v36
	v_and_b32_e32 v36, 48, v36
	s_movk_i32 s0, 0x90
	v_mul_lo_u32 v26, v26, s0
	v_lshrrev_b32_e32 v27, 3, v27
	v_lshrrev_b32_e32 v33, 3, v33
	v_add_u32_e32 v50, s26, v36
	v_and_or_b32 v36, v52, 32, v51
	v_add3_u32 v77, s26, v26, v0
	v_mul_lo_u32 v26, v32, s0
	v_mul_lo_u32 v27, v27, s0
	v_mul_lo_u32 v32, v33, s0
	v_mul_u32_u24_e32 v33, 0x48, v36
	v_add3_u32 v84, s26, v26, v0
	v_add3_u32 v85, s26, v27, v0
	v_add3_u32 v0, s26, v32, v0
	v_lshl_add_u32 v86, v33, 1, v50
	global_load_dwordx4 v[26:29], v[28:29], off offset:128
	s_nop 0
	global_load_dwordx4 v[30:33], v[30:31], off offset:128
	s_nop 0
	global_load_dwordx4 v[34:37], v[34:35], off offset:128
	s_nop 0
	global_load_dwordx4 v[38:41], v[38:39], off offset:128
	s_nop 0
	global_load_dwordx4 v[42:45], v[42:43], off offset:128
	s_nop 0
	global_load_dwordx4 v[46:49], v[46:47], off offset:128
	s_mov_b32 s1, 0xfffffc0
	s_and_b64 vcc, exec, s[46:47]
	s_waitcnt vmcnt(11)
	ds_write_b128 v77, v[2:5]
	s_waitcnt vmcnt(10)
	ds_write_b128 v84, v[6:9]
	s_waitcnt vmcnt(9)
	ds_write_b128 v85, v[10:13]
	s_waitcnt vmcnt(8)
	ds_write_b128 v0, v[14:17]
	s_waitcnt vmcnt(7)
	ds_write_b128 v77, v[18:21] offset:36864
	s_waitcnt vmcnt(6)
	ds_write_b128 v84, v[22:25] offset:36864
	s_waitcnt lgkmcnt(0)
	s_barrier
	ds_read_b128 v[2:5], v86 offset:36864
	ds_read_b128 v[58:61], v86 offset:39168
	v_and_or_b32 v6, v52, s1, v51
	v_mad_u64_u32 v[82:83], s[0:1], v6, s0, v[50:51]
	ds_read_b128 v[6:9], v82
	ds_read_b128 v[14:17], v82 offset:2304
	ds_read_b128 v[22:25], v82 offset:4608
	ds_read_b128 v[54:57], v82 offset:6912
	ds_read_b128 v[62:65], v86 offset:36928
	s_waitcnt lgkmcnt(4)
	v_mfma_f32_16x16x32_bf16 v[10:13], v[2:5], v[6:9], 0
	ds_read_b128 v[66:69], v82 offset:2368
	ds_read_b128 v[70:73], v82 offset:4672
	ds_read_b128 v[78:81], v82 offset:6976
	s_waitcnt lgkmcnt(6)
	v_mfma_f32_16x16x32_bf16 v[18:21], v[2:5], v[14:17], 0
	s_movk_i32 s0, 0x104
	s_waitcnt lgkmcnt(5)
	v_mfma_f32_16x16x32_bf16 v[50:53], v[2:5], v[22:25], 0
	s_waitcnt lgkmcnt(4)
	v_mfma_f32_16x16x32_bf16 v[2:5], v[2:5], v[54:57], 0
	v_mfma_f32_16x16x32_bf16 v[6:9], v[58:61], v[6:9], 0
	v_mfma_f32_16x16x32_bf16 v[14:17], v[58:61], v[14:17], 0
	v_mfma_f32_16x16x32_bf16 v[22:25], v[58:61], v[22:25], 0
	v_mfma_f32_16x16x32_bf16 v[54:57], v[58:61], v[54:57], 0
	ds_read_b128 v[58:61], v82 offset:64
	s_waitcnt lgkmcnt(0)
	v_mfma_f32_16x16x32_bf16 v[10:13], v[62:65], v[58:61], v[10:13]
	v_mfma_f32_16x16x32_bf16 v[18:21], v[62:65], v[66:69], v[18:21]
	v_mfma_f32_16x16x32_bf16 v[50:53], v[62:65], v[70:73], v[50:53]
	v_mfma_f32_16x16x32_bf16 v[2:5], v[62:65], v[78:81], v[2:5]
	ds_read_b128 v[62:65], v86 offset:39232
	s_waitcnt vmcnt(4)
	ds_write_b128 v77, v[30:33] offset:18432
	s_waitcnt vmcnt(0)
	ds_write_b128 v84, v[46:49] offset:18432
	ds_write_b128 v85, v[42:45] offset:18432
	ds_write_b128 v0, v[38:41] offset:18432
	ds_write_b128 v77, v[26:29] offset:46080
	ds_write_b128 v84, v[34:37] offset:46080
	s_waitcnt lgkmcnt(0)
	s_barrier
; DEVI int get_tid() { int t = threadIdx.x & 255; asm volatile("" : "+v"(t)); return t; }
; template <int BN, typename AF>
; DEVI void gemm_core(f32x4 (&acc)[BN / 32][4], AF arow, long a_kstride, const bfu* __restrict__ Bt, int ldb, int nkt,
;                     bfu* lds) {
;     ...
;   for (int kt = 0; kt < nkt; kt += 2) {
;     if (kt + 2 < nkt) G_LOAD(0, kt + 2);
;     COMPUTE(0);
;     if (kt + 1 < nkt) L_STORE(1, As + 128 * LS, Bs + BN * LS);
;     __syncthreads();
;     if (kt + 1 < nkt) {
;       if (kt + 3 < nkt) G_LOAD(1, kt + 3);
;       COMPUTE(1);
;       if (kt + 2 < nkt) L_STORE(0, As, Bs);
;       __syncthreads();
;     }
;   }
; DEVI void compress_item(const Params& p, int l, int ci, char* lds) {
;     ...
; #pragma unroll
;     for (int ni = 0; ni < 2; ++ni)
; #pragma unroll
;       for (int mi = 0; mi < 4; ++mi) {
;         int d = wn * 32 + ni * 16 + fq * 4;
;         int m = wm * 64 + mi * 16 + fr;
; #pragma unroll
;         for (int j = 0; j < 4; ++j) outs[m * 65 + d + j] = acc2[ni][mi][j];
;       }
;   }
;   __syncthreads();
;   if (kv == 0) {
;     if (writer && get_tid() < 128) {
;       int n = get_tid();
;       float ss = 0.f;
;       for (int d = 0; d < 64; ++d) { float v = outs[n * 65 + d]; ss += v * v; }
;       float rstd = rsqrtf(ss * (1.f / 64.f) + 1e-6f);
;       const float* kg = p.in[8] + (long)(l * 3 + 0) * 64;
;       bfu* dst = (bfu*)(p.ws + OFF_KCMP) + ((long)(b * 2 + h) * 128 + n) * 64;
;       for (int d = 0; d < 64; d += 2)
;         *(unsigned*)(dst + d) = pack2(outs[n * 65 + d] * rstd * kg[d], outs[n * 65 + d + 1] * rstd * kg[d + 1]);
;     }
;   } else {
;     bfu* dst = (bfu*)(p.ws + OFF_VCT) + (long)(b * 2 + h) * 64 * 128;
;     for (int id = get_tid(); writer && id < 64 * 128; id += 256) {
;       int d = id >> 7, n = id & 127;
;       dst[d * 128 + n] = f2bf(outs[n * 65 + d]);
	ds_read_b128 v[26:29], v86 offset:46080
	ds_read_b128 v[42:45], v82 offset:23040
	ds_read_b128 v[34:37], v82 offset:18432
	ds_read_b128 v[38:41], v82 offset:20736
	s_waitcnt lgkmcnt(2)
	v_mfma_f32_16x16x32_bf16 v[46:49], v[26:29], v[42:45], v[50:53]
	s_nop 2
	ds_read_b128 v[50:53], v82 offset:25344
	v_lshlrev_b32_e32 v0, 2, v75
	v_lshl_or_b32 v0, v74, 7, v0
	s_waitcnt lgkmcnt(2)
	v_mfma_f32_16x16x32_bf16 v[10:13], v[26:29], v[34:37], v[10:13]
	s_waitcnt lgkmcnt(1)
	v_mfma_f32_16x16x32_bf16 v[18:21], v[26:29], v[38:41], v[18:21]
	s_waitcnt lgkmcnt(0)
	v_mfma_f32_16x16x32_bf16 v[2:5], v[26:29], v[50:53], v[2:5]
	ds_read_b128 v[26:29], v86 offset:48384
	v_mfma_f32_16x16x32_bf16 v[6:9], v[62:65], v[58:61], v[6:9]
	v_mfma_f32_16x16x32_bf16 v[14:17], v[62:65], v[66:69], v[14:17]
	v_mfma_f32_16x16x32_bf16 v[22:25], v[62:65], v[70:73], v[22:25]
	v_mfma_f32_16x16x32_bf16 v[30:33], v[62:65], v[78:81], v[54:57]
	s_waitcnt lgkmcnt(0)
	v_mfma_f32_16x16x32_bf16 v[6:9], v[26:29], v[34:37], v[6:9]
	ds_read_b128 v[34:37], v86 offset:46144
	v_mfma_f32_16x16x32_bf16 v[14:17], v[26:29], v[38:41], v[14:17]
	ds_read_b128 v[38:41], v82 offset:20800
	v_mfma_f32_16x16x32_bf16 v[22:25], v[26:29], v[42:45], v[22:25]
	ds_read_b128 v[42:45], v82 offset:23104
	v_mfma_f32_16x16x32_bf16 v[26:29], v[26:29], v[50:53], v[30:33]
	ds_read_b128 v[50:53], v82 offset:25408
	s_nop 1
	ds_read_b128 v[30:33], v82 offset:18496
	s_waitcnt lgkmcnt(0)
	v_mfma_f32_16x16x32_bf16 v[10:13], v[34:37], v[30:33], v[10:13]
	v_mfma_f32_16x16x32_bf16 v[18:21], v[34:37], v[38:41], v[18:21]
	v_mfma_f32_16x16x32_bf16 v[46:49], v[34:37], v[42:45], v[46:49]
	v_mfma_f32_16x16x32_bf16 v[2:5], v[34:37], v[50:53], v[2:5]
	ds_read_b128 v[34:37], v86 offset:48448
	s_waitcnt lgkmcnt(0)
	s_barrier
	v_mfma_f32_16x16x32_bf16 v[6:9], v[34:37], v[30:33], v[6:9]
	v_mul_lo_u32 v30, v76, s0
	v_add3_u32 v0, s26, v0, v30
	ds_write2_b32 v0, v10, v11 offset1:1
	ds_write2_b32 v0, v12, v13 offset0:2 offset1:3
	v_add_u32_e32 v10, 0x1040, v0
	ds_write2_b32 v10, v18, v19 offset1:1
	v_add_u32_e32 v10, 0x1048, v0
	ds_write2_b32 v10, v20, v21 offset1:1
	v_add_u32_e32 v10, 0x2080, v0
	v_mfma_f32_16x16x32_bf16 v[14:17], v[34:37], v[38:41], v[14:17]
	ds_write2_b32 v10, v46, v47 offset1:1
	v_add_u32_e32 v10, 0x2088, v0
	ds_write2_b32 v10, v48, v49 offset1:1
	v_add_u32_e32 v10, 0x30c0, v0
	v_mfma_f32_16x16x32_bf16 v[22:25], v[34:37], v[42:45], v[22:25]
	ds_write2_b32 v10, v2, v3 offset1:1
	v_add_u32_e32 v2, 0x30c8, v0
	ds_write2_b32 v2, v4, v5 offset1:1
	ds_write2_b32 v0, v6, v7 offset0:16 offset1:17
	ds_write2_b32 v0, v8, v9 offset0:18 offset1:19
	v_add_u32_e32 v2, 0x1080, v0
	v_mfma_f32_16x16x32_bf16 v[26:29], v[34:37], v[50:53], v[26:29]
	ds_write2_b32 v2, v14, v15 offset1:1
	v_add_u32_e32 v2, 0x1088, v0
	ds_write2_b32 v2, v16, v17 offset1:1
	v_add_u32_e32 v2, 0x20c0, v0
	ds_write2_b32 v2, v22, v23 offset1:1
	v_add_u32_e32 v2, 0x20c8, v0
	ds_write2_b32 v2, v24, v25 offset1:1
	v_add_u32_e32 v2, 0x3100, v0
	v_add_u32_e32 v0, 0x3108, v0
	s_mov_b64 s[0:1], -1
	ds_write2_b32 v2, v26, v27 offset1:1
	ds_write2_b32 v0, v28, v29 offset1:1
	s_waitcnt lgkmcnt(0)
	s_barrier
	s_cbranch_vccz .LBB0_649
	v_mov_b32_e32 v2, v221
	s_movk_i32 s0, 0x2000
	s_nop 0
	v_cmp_gt_i32_e32 vcc, s0, v2
	s_and_b64 s[36:37], s[50:51], vcc
	s_and_saveexec_b64 s[0:1], s[36:37]
	s_cbranch_execz .LBB0_648
	v_and_b32_e32 v0, 0x7f, v2
	v_mov_b32_e32 v3, s26
	s_movk_i32 s11, 0x104
	v_mad_u32_u24 v0, v0, s11, v3
	v_max_i32_e32 v3, 0x1f00, v2
	v_sub_u32_e32 v3, v3, v2
	v_add_u32_e32 v3, 0xff, v3
	s_movk_i32 s11, 0xff
	v_cmp_lt_u32_e32 vcc, s11, v3
	s_mov_b64 s[40:41], -1
	s_and_saveexec_b64 s[36:37], vcc
	s_cbranch_execz .LBB0_645
	v_lshrrev_b32_e32 v3, 8, v3
	s_lshl_b32 s20, s42, 14
	v_add_u32_e32 v6, 1, v3
	s_and_b32 s20, s20, 0x3c000
	v_readlane_b32 s11, v243, 16
	s_add_u32 s40, s11, s20
	v_readlane_b32 s11, v243, 17
	v_and_b32_e32 v7, 0x1fffffe, v6
	v_add_u32_e32 v3, 0x100, v2
	s_addc_u32 s41, s11, 0
	s_mov_b64 s[46:47], 0
	v_mov_b32_e32 v8, v7
	v_mov_b64_e32 v[4:5], v[2:3]
	s_movk_i32 s11, 0x7fff
